# indexer key transform done with packed 16-bit ops (shift/or/xor) instead of per-half compare/select
# speedup vs baseline: 1.0052x; 1.0052x over previous
.LBB0_639:
	s_waitcnt vmcnt(2)
	v_mov_b64_e32 v[134:135], v[78:79]
	v_mov_b64_e32 v[132:133], v[76:77]
	v_mov_b64_e32 v[130:131], v[74:75]
	v_mov_b64_e32 v[128:129], v[72:73]
	s_add_i32 s0, s9, 1
	v_min_i32_e32 v72, s0, v139
	s_add_i32 s0, s9, 2
	v_min_i32_e32 v88, s0, v139
	s_add_i32 s0, s9, 3
	s_add_i32 s8, s9, 4
	v_min_i32_e32 v96, s0, v139
	v_min_i32_e32 v104, s8, v139
	v_lshl_add_u32 v72, v72, 6, v138
	v_lshl_add_u32 v88, v88, 6, v138
	v_lshl_add_u32 v96, v96, 6, v138
	v_lshl_add_u32 v104, v104, 6, v138
	v_ashrrev_i32_e32 v73, 31, v72
	v_ashrrev_i32_e32 v89, 31, v88
	v_ashrrev_i32_e32 v97, 31, v96
	v_ashrrev_i32_e32 v105, 31, v104
	v_lshlrev_b64 v[72:73], 7, v[72:73]
	v_lshlrev_b64 v[88:89], 7, v[88:89]
	v_lshlrev_b64 v[96:97], 7, v[96:97]
	v_lshlrev_b64 v[104:105], 7, v[104:105]
	v_lshl_add_u64 v[72:73], v[140:141], 0, v[72:73]
	v_lshl_add_u64 v[92:93], v[140:141], 0, v[88:89]
	v_lshl_add_u64 v[100:101], v[140:141], 0, v[96:97]
	v_lshl_add_u64 v[108:109], v[140:141], 0, v[104:105]
	global_load_dwordx4 v[76:79], v[72:73], off
	s_nop 0
	global_load_dwordx4 v[72:75], v[72:73], off offset:64
	s_nop 0
	global_load_dwordx4 v[88:91], v[92:93], off
	s_nop 0
	global_load_dwordx4 v[92:95], v[92:93], off offset:64
	s_nop 0
	global_load_dwordx4 v[96:99], v[100:101], off
	s_nop 0
	global_load_dwordx4 v[100:103], v[100:101], off offset:64
	s_nop 0
	global_load_dwordx4 v[104:107], v[108:109], off
	s_nop 0
	global_load_dwordx4 v[108:111], v[108:109], off offset:64
	v_mfma_f32_16x16x32_bf16 v[200:203], v[132:135], v[68:71], 0
	v_mfma_f32_16x16x32_bf16 v[200:203], v[128:131], v[64:67], v[200:203]
	v_mfma_f32_16x16x32_bf16 v[204:207], v[132:135], v[60:63], 0
	v_mfma_f32_16x16x32_bf16 v[204:207], v[128:131], v[56:59], v[204:207]
	v_mfma_f32_16x16x32_bf16 v[208:211], v[132:135], v[52:55], 0
	v_mfma_f32_16x16x32_bf16 v[208:211], v[128:131], v[48:51], v[208:211]
	s_nop 3
	v_max_f32_e32 v212, 0, v200
	v_max_f32_e32 v213, 0, v201
	v_max_f32_e32 v214, 0, v202
	v_max_f32_e32 v215, 0, v203
	v_pk_fma_f32 v[216:217], v[0:1], v[212:213], 0 op_sel_hi:[1,1,0]
	v_pk_fma_f32 v[218:219], v[0:1], v[214:215], 0 op_sel_hi:[1,1,0]
	v_mfma_f32_16x16x32_bf16 v[200:203], v[132:135], v[44:47], 0
	v_mfma_f32_16x16x32_bf16 v[200:203], v[128:131], v[40:43], v[200:203]
	v_max_f32_e32 v212, 0, v204
	v_max_f32_e32 v213, 0, v205
	v_max_f32_e32 v214, 0, v206
	v_max_f32_e32 v215, 0, v207
	v_pk_fma_f32 v[216:217], v[148:149], v[212:213], v[216:217]
	v_pk_fma_f32 v[218:219], v[148:149], v[214:215], v[218:219]
	v_mfma_f32_16x16x32_bf16 v[204:207], v[132:135], v[36:39], 0
	v_mfma_f32_16x16x32_bf16 v[204:207], v[128:131], v[32:35], v[204:207]
	v_max_f32_e32 v212, 0, v208
	v_max_f32_e32 v213, 0, v209
	v_max_f32_e32 v214, 0, v210
	v_max_f32_e32 v215, 0, v211
	v_pk_fma_f32 v[216:217], v[142:143], v[212:213], v[216:217]
	v_pk_fma_f32 v[218:219], v[142:143], v[214:215], v[218:219]
	v_mfma_f32_16x16x32_bf16 v[208:211], v[132:135], v[28:31], 0
	v_mfma_f32_16x16x32_bf16 v[208:211], v[128:131], v[24:27], v[208:211]
	v_max_f32_e32 v212, 0, v200
	v_max_f32_e32 v213, 0, v201
	v_max_f32_e32 v214, 0, v202
	v_max_f32_e32 v215, 0, v203
	v_pk_fma_f32 v[216:217], v[2:3], v[212:213], v[216:217]
	v_pk_fma_f32 v[218:219], v[2:3], v[214:215], v[218:219]
	v_mfma_f32_16x16x32_bf16 v[200:203], v[132:135], v[20:23], 0
	v_mfma_f32_16x16x32_bf16 v[200:203], v[128:131], v[16:19], v[200:203]
	v_max_f32_e32 v212, 0, v204
	v_max_f32_e32 v213, 0, v205
	v_max_f32_e32 v214, 0, v206
	v_max_f32_e32 v215, 0, v207
	v_pk_fma_f32 v[216:217], v[144:145], v[212:213], v[216:217]
	v_pk_fma_f32 v[218:219], v[144:145], v[214:215], v[218:219]
	v_mfma_f32_16x16x32_bf16 v[204:207], v[132:135], v[12:15], 0
	v_mfma_f32_16x16x32_bf16 v[204:207], v[128:131], v[8:11], v[204:207]
	v_max_f32_e32 v212, 0, v208
	v_max_f32_e32 v213, 0, v209
	v_max_f32_e32 v214, 0, v210
	v_max_f32_e32 v215, 0, v211
	v_pk_fma_f32 v[216:217], v[4:5], v[212:213], v[216:217]
	v_pk_fma_f32 v[218:219], v[4:5], v[214:215], v[218:219]
	v_max_f32_e32 v212, 0, v200
	v_max_f32_e32 v213, 0, v201
	v_max_f32_e32 v214, 0, v202
	v_max_f32_e32 v215, 0, v203
	v_pk_fma_f32 v[216:217], v[146:147], v[212:213], v[216:217]
	v_pk_fma_f32 v[218:219], v[146:147], v[214:215], v[218:219]
	v_max_f32_e32 v212, 0, v204
	v_max_f32_e32 v213, 0, v205
	v_max_f32_e32 v214, 0, v206
	v_max_f32_e32 v215, 0, v207
	v_pk_fma_f32 v[216:217], v[6:7], v[212:213], v[216:217]
	v_pk_fma_f32 v[218:219], v[6:7], v[214:215], v[218:219]
	v_cvt_pk_f16_f32 v228, v216, v217
	v_cvt_pk_f16_f32 v229, v218, v219
	v_pk_ashrrev_i16 v220, 15, v228 op_sel_hi:[0,1]
	v_pk_ashrrev_i16 v221, 15, v229 op_sel_hi:[0,1]
	v_or_b32_e32 v220, 0x80008000, v220
	v_or_b32_e32 v221, 0x80008000, v221
	v_xor_b32_e32 v228, v228, v220
	v_xor_b32_e32 v229, v229, v221
	ds_write_b64 v158, v[228:229]
	s_add_i32 s0, s9, -2
	v_cmp_lt_i32_e32 vcc, s0, v156
	s_and_saveexec_b64 s[6:7], vcc
	s_cbranch_execz .LBB0_641
	s_waitcnt vmcnt(8)
	v_mfma_f32_16x16x32_bf16 v[200:203], v[124:127], v[68:71], 0
	v_mfma_f32_16x16x32_bf16 v[200:203], v[120:123], v[64:67], v[200:203]
	v_mfma_f32_16x16x32_bf16 v[204:207], v[124:127], v[60:63], 0
	v_mfma_f32_16x16x32_bf16 v[204:207], v[120:123], v[56:59], v[204:207]
	v_mfma_f32_16x16x32_bf16 v[208:211], v[124:127], v[52:55], 0
	v_mfma_f32_16x16x32_bf16 v[208:211], v[120:123], v[48:51], v[208:211]
	s_nop 3
	v_max_f32_e32 v212, 0, v200
	v_max_f32_e32 v213, 0, v201
	v_max_f32_e32 v214, 0, v202
	v_max_f32_e32 v215, 0, v203
	v_pk_fma_f32 v[216:217], v[0:1], v[212:213], 0 op_sel_hi:[1,1,0]
	v_pk_fma_f32 v[218:219], v[0:1], v[214:215], 0 op_sel_hi:[1,1,0]
	v_mfma_f32_16x16x32_bf16 v[200:203], v[124:127], v[44:47], 0
	v_mfma_f32_16x16x32_bf16 v[200:203], v[120:123], v[40:43], v[200:203]
	v_max_f32_e32 v212, 0, v204
	v_max_f32_e32 v213, 0, v205
	v_max_f32_e32 v214, 0, v206
	v_max_f32_e32 v215, 0, v207
	v_pk_fma_f32 v[216:217], v[148:149], v[212:213], v[216:217]
	v_pk_fma_f32 v[218:219], v[148:149], v[214:215], v[218:219]
	v_mfma_f32_16x16x32_bf16 v[204:207], v[124:127], v[36:39], 0
	v_mfma_f32_16x16x32_bf16 v[204:207], v[120:123], v[32:35], v[204:207]
	v_max_f32_e32 v212, 0, v208
	v_max_f32_e32 v213, 0, v209
	v_max_f32_e32 v214, 0, v210
	v_max_f32_e32 v215, 0, v211
	v_pk_fma_f32 v[216:217], v[142:143], v[212:213], v[216:217]
	v_pk_fma_f32 v[218:219], v[142:143], v[214:215], v[218:219]
	v_mfma_f32_16x16x32_bf16 v[208:211], v[124:127], v[28:31], 0
	v_mfma_f32_16x16x32_bf16 v[208:211], v[120:123], v[24:27], v[208:211]
	v_max_f32_e32 v212, 0, v200
	v_max_f32_e32 v213, 0, v201
	v_max_f32_e32 v214, 0, v202
	v_max_f32_e32 v215, 0, v203
	v_pk_fma_f32 v[216:217], v[2:3], v[212:213], v[216:217]
	v_pk_fma_f32 v[218:219], v[2:3], v[214:215], v[218:219]
	v_mfma_f32_16x16x32_bf16 v[200:203], v[124:127], v[20:23], 0
	v_mfma_f32_16x16x32_bf16 v[200:203], v[120:123], v[16:19], v[200:203]
	v_max_f32_e32 v212, 0, v204
	v_max_f32_e32 v213, 0, v205
	v_max_f32_e32 v214, 0, v206
	v_max_f32_e32 v215, 0, v207
	v_pk_fma_f32 v[216:217], v[144:145], v[212:213], v[216:217]
	v_pk_fma_f32 v[218:219], v[144:145], v[214:215], v[218:219]
	v_mfma_f32_16x16x32_bf16 v[204:207], v[124:127], v[12:15], 0
	v_mfma_f32_16x16x32_bf16 v[204:207], v[120:123], v[8:11], v[204:207]
	v_max_f32_e32 v212, 0, v208
	v_max_f32_e32 v213, 0, v209
	v_max_f32_e32 v214, 0, v210
	v_max_f32_e32 v215, 0, v211
	v_pk_fma_f32 v[216:217], v[4:5], v[212:213], v[216:217]
	v_pk_fma_f32 v[218:219], v[4:5], v[214:215], v[218:219]
	v_max_f32_e32 v212, 0, v200
	v_max_f32_e32 v213, 0, v201
	v_max_f32_e32 v214, 0, v202
	v_max_f32_e32 v215, 0, v203
	v_pk_fma_f32 v[216:217], v[146:147], v[212:213], v[216:217]
	v_pk_fma_f32 v[218:219], v[146:147], v[214:215], v[218:219]
	v_max_f32_e32 v212, 0, v204
	v_max_f32_e32 v213, 0, v205
	v_max_f32_e32 v214, 0, v206
	v_max_f32_e32 v215, 0, v207
	v_pk_fma_f32 v[216:217], v[6:7], v[212:213], v[216:217]
	v_pk_fma_f32 v[218:219], v[6:7], v[214:215], v[218:219]
	v_cvt_pk_f16_f32 v228, v216, v217
	v_cvt_pk_f16_f32 v229, v218, v219
	v_pk_ashrrev_i16 v220, 15, v228 op_sel_hi:[0,1]
	v_pk_ashrrev_i16 v221, 15, v229 op_sel_hi:[0,1]
	v_or_b32_e32 v220, 0x80008000, v220
	v_or_b32_e32 v221, 0x80008000, v221
	v_xor_b32_e32 v228, v228, v220
	v_xor_b32_e32 v229, v229, v221
	ds_write_b64 v158, v[228:229] offset:128
.LBB0_641:
	s_or_b64 exec, exec, s[6:7]
	s_add_i32 s0, s9, -1
	v_cmp_lt_i32_e32 vcc, s0, v156
	s_and_saveexec_b64 s[6:7], vcc
	s_cbranch_execz .LBB0_643
	s_waitcnt vmcnt(8)
	v_mfma_f32_16x16x32_bf16 v[200:203], v[116:119], v[68:71], 0
	v_mfma_f32_16x16x32_bf16 v[200:203], v[112:115], v[64:67], v[200:203]
	v_mfma_f32_16x16x32_bf16 v[204:207], v[116:119], v[60:63], 0
	v_mfma_f32_16x16x32_bf16 v[204:207], v[112:115], v[56:59], v[204:207]
	v_mfma_f32_16x16x32_bf16 v[208:211], v[116:119], v[52:55], 0
	v_mfma_f32_16x16x32_bf16 v[208:211], v[112:115], v[48:51], v[208:211]
	s_nop 3
	v_max_f32_e32 v212, 0, v200
	v_max_f32_e32 v213, 0, v201
	v_max_f32_e32 v214, 0, v202
	v_max_f32_e32 v215, 0, v203
	v_pk_fma_f32 v[216:217], v[0:1], v[212:213], 0 op_sel_hi:[1,1,0]
	v_pk_fma_f32 v[218:219], v[0:1], v[214:215], 0 op_sel_hi:[1,1,0]
	v_mfma_f32_16x16x32_bf16 v[200:203], v[116:119], v[44:47], 0
	v_mfma_f32_16x16x32_bf16 v[200:203], v[112:115], v[40:43], v[200:203]
	v_max_f32_e32 v212, 0, v204
	v_max_f32_e32 v213, 0, v205
	v_max_f32_e32 v214, 0, v206
	v_max_f32_e32 v215, 0, v207
	v_pk_fma_f32 v[216:217], v[148:149], v[212:213], v[216:217]
	v_pk_fma_f32 v[218:219], v[148:149], v[214:215], v[218:219]
	v_mfma_f32_16x16x32_bf16 v[204:207], v[116:119], v[36:39], 0
	v_mfma_f32_16x16x32_bf16 v[204:207], v[112:115], v[32:35], v[204:207]
	v_max_f32_e32 v212, 0, v208
	v_max_f32_e32 v213, 0, v209
	v_max_f32_e32 v214, 0, v210
	v_max_f32_e32 v215, 0, v211
	v_pk_fma_f32 v[216:217], v[142:143], v[212:213], v[216:217]
	v_pk_fma_f32 v[218:219], v[142:143], v[214:215], v[218:219]
	v_mfma_f32_16x16x32_bf16 v[208:211], v[116:119], v[28:31], 0
	v_mfma_f32_16x16x32_bf16 v[208:211], v[112:115], v[24:27], v[208:211]
	v_max_f32_e32 v212, 0, v200
	v_max_f32_e32 v213, 0, v201
	v_max_f32_e32 v214, 0, v202
	v_max_f32_e32 v215, 0, v203
	v_pk_fma_f32 v[216:217], v[2:3], v[212:213], v[216:217]
	v_pk_fma_f32 v[218:219], v[2:3], v[214:215], v[218:219]
	v_mfma_f32_16x16x32_bf16 v[200:203], v[116:119], v[20:23], 0
	v_mfma_f32_16x16x32_bf16 v[200:203], v[112:115], v[16:19], v[200:203]
	v_max_f32_e32 v212, 0, v204
	v_max_f32_e32 v213, 0, v205
	v_max_f32_e32 v214, 0, v206
	v_max_f32_e32 v215, 0, v207
	v_pk_fma_f32 v[216:217], v[144:145], v[212:213], v[216:217]
	v_pk_fma_f32 v[218:219], v[144:145], v[214:215], v[218:219]
	v_mfma_f32_16x16x32_bf16 v[204:207], v[116:119], v[12:15], 0
	v_mfma_f32_16x16x32_bf16 v[204:207], v[112:115], v[8:11], v[204:207]
	v_max_f32_e32 v212, 0, v208
	v_max_f32_e32 v213, 0, v209
	v_max_f32_e32 v214, 0, v210
	v_max_f32_e32 v215, 0, v211
	v_pk_fma_f32 v[216:217], v[4:5], v[212:213], v[216:217]
	v_pk_fma_f32 v[218:219], v[4:5], v[214:215], v[218:219]
	v_max_f32_e32 v212, 0, v200
	v_max_f32_e32 v213, 0, v201
	v_max_f32_e32 v214, 0, v202
	v_max_f32_e32 v215, 0, v203
	v_pk_fma_f32 v[216:217], v[146:147], v[212:213], v[216:217]
	v_pk_fma_f32 v[218:219], v[146:147], v[214:215], v[218:219]
	v_max_f32_e32 v212, 0, v204
	v_max_f32_e32 v213, 0, v205
	v_max_f32_e32 v214, 0, v206
	v_max_f32_e32 v215, 0, v207
	v_pk_fma_f32 v[216:217], v[6:7], v[212:213], v[216:217]
	v_pk_fma_f32 v[218:219], v[6:7], v[214:215], v[218:219]
	v_cvt_pk_f16_f32 v228, v216, v217
	v_cvt_pk_f16_f32 v229, v218, v219
	v_pk_ashrrev_i16 v220, 15, v228 op_sel_hi:[0,1]
	v_pk_ashrrev_i16 v221, 15, v229 op_sel_hi:[0,1]
	v_or_b32_e32 v220, 0x80008000, v220
	v_or_b32_e32 v221, 0x80008000, v221
	v_xor_b32_e32 v228, v228, v220
	v_xor_b32_e32 v229, v229, v221
	ds_write_b64 v158, v[228:229] offset:256
.LBB0_643:
	s_or_b64 exec, exec, s[6:7]
	v_cmp_lt_i32_e32 vcc, s9, v156
	s_and_saveexec_b64 s[6:7], vcc
	s_cbranch_execz .LBB0_638
	s_waitcnt vmcnt(8)
	v_mfma_f32_16x16x32_bf16 v[200:203], v[84:87], v[68:71], 0
	v_mfma_f32_16x16x32_bf16 v[200:203], v[80:83], v[64:67], v[200:203]
	v_mfma_f32_16x16x32_bf16 v[204:207], v[84:87], v[60:63], 0
	v_mfma_f32_16x16x32_bf16 v[204:207], v[80:83], v[56:59], v[204:207]
	v_mfma_f32_16x16x32_bf16 v[208:211], v[84:87], v[52:55], 0
	v_mfma_f32_16x16x32_bf16 v[208:211], v[80:83], v[48:51], v[208:211]
	s_nop 3
	v_max_f32_e32 v212, 0, v200
	v_max_f32_e32 v213, 0, v201
	v_max_f32_e32 v214, 0, v202
	v_max_f32_e32 v215, 0, v203
	v_pk_fma_f32 v[216:217], v[0:1], v[212:213], 0 op_sel_hi:[1,1,0]
	v_pk_fma_f32 v[218:219], v[0:1], v[214:215], 0 op_sel_hi:[1,1,0]
	v_mfma_f32_16x16x32_bf16 v[200:203], v[84:87], v[44:47], 0
	v_mfma_f32_16x16x32_bf16 v[200:203], v[80:83], v[40:43], v[200:203]
	v_max_f32_e32 v212, 0, v204
	v_max_f32_e32 v213, 0, v205
	v_max_f32_e32 v214, 0, v206
	v_max_f32_e32 v215, 0, v207
	v_pk_fma_f32 v[216:217], v[148:149], v[212:213], v[216:217]
	v_pk_fma_f32 v[218:219], v[148:149], v[214:215], v[218:219]
	v_mfma_f32_16x16x32_bf16 v[204:207], v[84:87], v[36:39], 0
	v_mfma_f32_16x16x32_bf16 v[204:207], v[80:83], v[32:35], v[204:207]
	v_max_f32_e32 v212, 0, v208
	v_max_f32_e32 v213, 0, v209
	v_max_f32_e32 v214, 0, v210
	v_max_f32_e32 v215, 0, v211
	v_pk_fma_f32 v[216:217], v[142:143], v[212:213], v[216:217]
	v_pk_fma_f32 v[218:219], v[142:143], v[214:215], v[218:219]
	v_mfma_f32_16x16x32_bf16 v[208:211], v[84:87], v[28:31], 0
	v_mfma_f32_16x16x32_bf16 v[208:211], v[80:83], v[24:27], v[208:211]
	v_max_f32_e32 v212, 0, v200
	v_max_f32_e32 v213, 0, v201
	v_max_f32_e32 v214, 0, v202
	v_max_f32_e32 v215, 0, v203
	v_pk_fma_f32 v[216:217], v[2:3], v[212:213], v[216:217]
	v_pk_fma_f32 v[218:219], v[2:3], v[214:215], v[218:219]
	v_mfma_f32_16x16x32_bf16 v[200:203], v[84:87], v[20:23], 0
	v_mfma_f32_16x16x32_bf16 v[200:203], v[80:83], v[16:19], v[200:203]
	v_max_f32_e32 v212, 0, v204
	v_max_f32_e32 v213, 0, v205
	v_max_f32_e32 v214, 0, v206
	v_max_f32_e32 v215, 0, v207
	v_pk_fma_f32 v[216:217], v[144:145], v[212:213], v[216:217]
	v_pk_fma_f32 v[218:219], v[144:145], v[214:215], v[218:219]
	v_mfma_f32_16x16x32_bf16 v[204:207], v[84:87], v[12:15], 0
	v_mfma_f32_16x16x32_bf16 v[204:207], v[80:83], v[8:11], v[204:207]
	v_max_f32_e32 v212, 0, v208
	v_max_f32_e32 v213, 0, v209
	v_max_f32_e32 v214, 0, v210
	v_max_f32_e32 v215, 0, v211
	v_pk_fma_f32 v[216:217], v[4:5], v[212:213], v[216:217]
	v_pk_fma_f32 v[218:219], v[4:5], v[214:215], v[218:219]
	v_max_f32_e32 v212, 0, v200
	v_max_f32_e32 v213, 0, v201
	v_max_f32_e32 v214, 0, v202
	v_max_f32_e32 v215, 0, v203
	v_pk_fma_f32 v[216:217], v[146:147], v[212:213], v[216:217]
	v_pk_fma_f32 v[218:219], v[146:147], v[214:215], v[218:219]
	v_max_f32_e32 v212, 0, v204
	v_max_f32_e32 v213, 0, v205
	v_max_f32_e32 v214, 0, v206
	v_max_f32_e32 v215, 0, v207
	v_pk_fma_f32 v[216:217], v[6:7], v[212:213], v[216:217]
	v_pk_fma_f32 v[218:219], v[6:7], v[214:215], v[218:219]
	v_cvt_pk_f16_f32 v228, v216, v217
	v_cvt_pk_f16_f32 v229, v218, v219
	v_pk_ashrrev_i16 v220, 15, v228 op_sel_hi:[0,1]
	v_pk_ashrrev_i16 v221, 15, v229 op_sel_hi:[0,1]
	v_or_b32_e32 v220, 0x80008000, v220
	v_or_b32_e32 v221, 0x80008000, v221
	v_xor_b32_e32 v228, v228, v220
	v_xor_b32_e32 v229, v229, v221
	ds_write_b64 v158, v[228:229] offset:384
	s_branch .LBB0_638
